# v17 + step B: row-sum adds put back behind their exps, 12 of the 16 P packs moved into the last MFMA gaps
# speedup vs baseline: 1.0632x; 1.0030x over previous
.LBB0_466:
	s_cmp_lt_i32 s78, s39
	s_cselect_b64 s[80:81], -1, 0
	v_cndmask_b32_e64 v228, -v201, v201, s[80:81]
	s_and_b64 s[80:81], s[80:81], exec
	s_cselect_b32 s60, s78, s61
	s_add_i32 s60, s60, s33
	s_lshl_b32 s78, s60, 6
	s_ashr_i32 s79, s78, 31
	s_lshl_b64 s[80:81], s[78:79], 1
	s_addk_i32 s62, 0xc000
	s_cmp_lg_u32 s5, 0
	s_cselect_b32 s60, s62, 0x8000
	s_add_i32 s60, s14, s60
	v_lshl_add_u64 v[66:67], v[204:205], 0, s[80:81]
	s_add_i32 m0, s60, 0xc000
	v_lshl_add_u64 v[68:69], v[206:207], 0, s[80:81]
	global_load_lds_dwordx4 v[66:67], off
	s_add_i32 m0, s60, 0xc400
	v_cvt_f32_i32_e32 v66, s78
	global_load_lds_dwordx4 v[68:69], off
	v_exp_f32_e32 v231, v98
	v_add_f32_e32 v66, v155, v66
	v_fma_f32 v230, v228, v66, -v199
	v_add_u32_e32 v229, s10, v218
	v_exp_f32_e32 v233, v114
	v_fma_f32 v66, 0, v228, v230
	v_exp_f32_e32 v234, v99
	v_exp_f32_e32 v235, v115
	v_add_f32_e32 v67, v228, v230
	v_exp_f32_e32 v236, v100
	v_exp_f32_e32 v237, v116
	v_exp_f32_e32 v238, v101
	v_exp_f32_e32 v239, v117
	v_fma_f32 v68, v228, s64, v230
	v_fma_f32 v69, v228, s65, v230
	v_fma_f32 v70, v228, s66, v230
	v_fma_f32 v71, v228, s67, v230
	v_cvt_pk_bf16_f32 v98, v249, v250
	v_cvt_pk_bf16_f32 v99, v195, v251
	v_cvt_pk_bf16_f32 v100, v252, v253
	v_cvt_pk_bf16_f32 v101, v72, v73
	v_cvt_pk_bf16_f32 v114, v90, v91
	v_cvt_pk_bf16_f32 v115, v92, v93
	v_cvt_pk_bf16_f32 v116, v94, v95
	v_cvt_pk_bf16_f32 v117, v96, v97
	v_mul_f32_e32 v232, 0x42000000, v228
	v_exp_f32_e32 v240, v102
	v_exp_f32_e32 v241, v118
	v_exp_f32_e32 v242, v103
	v_exp_f32_e32 v243, v119
	ds_read_b128 v[90:93], v227 offset:53248
	s_waitcnt lgkmcnt(3)
	v_mfma_f32_32x32x16_bf16 v[18:33], v[86:89], v[74:77], v[18:33]
	v_add_f32_e32 v254, 0, v231
	v_add_f32_e32 v254, v233, v254
	v_fma_f32 v72, v228, s68, v230
	v_fma_f32 v73, v228, s69, v230
	v_exp_f32_e32 v181, v104
	v_exp_f32_e32 v183, v120
	ds_read_b128 v[86:89], v227 offset:57344
	s_waitcnt lgkmcnt(3)
	v_mfma_f32_32x32x16_bf16 v[2:17], v[82:85], v[74:77], v[2:17]
	v_add_f32_e32 v254, v234, v254
	v_add_f32_e32 v254, v235, v254
	v_exp_f32_e32 v195, v105
	v_exp_f32_e32 v200, v121
	ds_read_b128 v[82:85], v227 offset:61440
	s_waitcnt lgkmcnt(3)
	v_mfma_f32_32x32x16_bf16 v[50:65], v[78:81], v[98:101], v[50:65]
	v_add_f32_e32 v254, v236, v254
	v_add_f32_e32 v254, v237, v254
	v_fma_f32 v74, v228, s70, v230
	v_fma_f32 v75, v228, s71, v230
	v_exp_f32_e32 v224, v106
	v_exp_f32_e32 v122, v122
	v_add_u32_e32 v78, v198, v226
	ds_read_b128 v[94:97], v78 offset:49152
	s_waitcnt lgkmcnt(3)
	v_mfma_f32_32x32x16_bf16 v[34:49], v[90:93], v[98:101], v[34:49]
	v_add_f32_e32 v254, v238, v254
	v_add_f32_e32 v254, v239, v254
	v_exp_f32_e32 v225, v107
	v_exp_f32_e32 v123, v123
	ds_read_b128 v[90:93], v78 offset:53248
	s_waitcnt lgkmcnt(3)
	v_mfma_f32_32x32x16_bf16 v[18:33], v[86:89], v[98:101], v[18:33]
	v_add_f32_e32 v254, v240, v254
	v_add_f32_e32 v254, v241, v254
	v_fma_f32 v76, v228, s72, v230
	v_fma_f32 v77, v228, s73, v230
	v_exp_f32_e32 v227, v108
	v_exp_f32_e32 v124, v124
	ds_read_b128 v[86:89], v78 offset:57344
	s_waitcnt lgkmcnt(3)
	v_mfma_f32_32x32x16_bf16 v[2:17], v[82:85], v[98:101], v[2:17]
	v_add_f32_e32 v254, v242, v254
	v_add_f32_e32 v254, v243, v254
	v_exp_f32_e32 v244, v109
	v_exp_f32_e32 v125, v125
	ds_read_b128 v[98:101], v78 offset:61440
	s_waitcnt lgkmcnt(3)
	v_mfma_f32_32x32x16_bf16 v[50:65], v[94:97], v[114:117], v[50:65]
	v_add_f32_e32 v254, v181, v254
	v_add_f32_e32 v254, v183, v254
	v_fma_f32 v78, v228, s74, v230
	v_fma_f32 v79, v228, s75, v230
	v_exp_f32_e32 v245, v110
	v_exp_f32_e32 v126, v126
	v_add_u32_e32 v80, v229, v149
	ds_read_b128 v[102:105], v80
	s_waitcnt lgkmcnt(3)
	v_mfma_f32_32x32x16_bf16 v[34:49], v[90:93], v[114:117], v[34:49]
	v_add_f32_e32 v254, v195, v254
	v_add_f32_e32 v254, v200, v254
	v_exp_f32_e32 v246, v111
	v_exp_f32_e32 v127, v127
	ds_read_b128 v[106:109], v80 offset:4096
	s_waitcnt lgkmcnt(3)
	v_mfma_f32_32x32x16_bf16 v[18:33], v[86:89], v[114:117], v[18:33]
	v_add_f32_e32 v254, v224, v254
	v_add_f32_e32 v254, v122, v254
	v_fma_f32 v80, v228, s76, v230
	v_fma_f32 v81, v228, s77, v230
	v_exp_f32_e32 v247, v112
	v_exp_f32_e32 v128, v128
	v_add_u32_e32 v110, v229, v208
	ds_read_b128 v[118:121], v110
	s_waitcnt lgkmcnt(3)
	v_mfma_f32_32x32x16_bf16 v[2:17], v[98:101], v[114:117], v[2:17]
	v_add_f32_e32 v254, v225, v254
	v_add_f32_e32 v254, v123, v254
	v_add_f32_e64 v82, v232, v66
	v_add_f32_e64 v83, v232, v67
	v_add_f32_e64 v96, v232, v80
	v_add_f32_e64 v97, v232, v81
	v_add_f32_e64 v94, v232, v78
	v_add_f32_e64 v95, v232, v79
	v_add_f32_e32 v92, v232, v76
	v_add_f32_e32 v93, v232, v77
	v_add_f32_e32 v90, v232, v74
	v_add_f32_e32 v91, v232, v75
	v_add_f32_e32 v88, v232, v72
	v_add_f32_e32 v89, v232, v73
	v_add_f32_e32 v86, v232, v70
	v_add_f32_e32 v87, v232, v71
	v_add_f32_e32 v84, v232, v68
	v_add_f32_e32 v85, v232, v69
	v_exp_f32_e32 v228, v113
	v_exp_f32_e32 v129, v129
	ds_read_b128 v[98:101], v110 offset:4096
	s_waitcnt lgkmcnt(3)
	v_mfma_f32_32x32x16_bf16 v[66:81], v[102:105], v[130:133], v[66:81]
	v_add_f32_e32 v254, v227, v254
	v_add_f32_e32 v254, v124, v254
	v_add_f32_e32 v254, v244, v254
	v_add_u32_e32 v110, v229, v209
	ds_read_b128 v[102:105], v110
	s_waitcnt lgkmcnt(3)
	v_mfma_f32_32x32x16_bf16 v[82:97], v[106:109], v[130:133], v[82:97]
	v_add_f32_e32 v254, v125, v254
	v_add_f32_e32 v254, v245, v254
	v_add_f32_e32 v254, v126, v254
	ds_read_b128 v[106:109], v110 offset:4096
	s_waitcnt lgkmcnt(3)
	v_mfma_f32_32x32x16_bf16 v[66:81], v[118:121], v[134:137], v[66:81]
	v_add_f32_e32 v254, v246, v254
	v_add_f32_e32 v254, v127, v254
	v_add_f32_e32 v254, v247, v254
	v_add_u32_e32 v114, v229, v226
	ds_read_b128 v[110:113], v114
	s_waitcnt lgkmcnt(3)
	v_mfma_f32_32x32x16_bf16 v[82:97], v[98:101], v[134:137], v[82:97]
	v_add_f32_e32 v254, v128, v254
	v_add_f32_e32 v254, v228, v254
	v_add_f32_e32 v254, v129, v254
	ds_read_b128 v[98:101], v114 offset:4096
	s_waitcnt lgkmcnt(3)
	v_mfma_f32_32x32x16_bf16 v[66:81], v[102:105], v[138:141], v[66:81]
	v_cvt_pk_bf16_f32 v114, v122, v123
	v_cvt_pk_bf16_f32 v115, v124, v125
	v_cvt_pk_bf16_f32 v116, v126, v127
	v_cvt_pk_bf16_f32 v117, v128, v129
	s_waitcnt lgkmcnt(2)
	v_mfma_f32_32x32x16_bf16 v[82:97], v[106:109], v[138:141], v[82:97]
	v_cvt_pk_bf16_f32 v106, v224, v225
	v_cvt_pk_bf16_f32 v107, v227, v244
	v_cvt_pk_bf16_f32 v108, v245, v246
	v_cvt_pk_bf16_f32 v109, v247, v228
	s_waitcnt lgkmcnt(1)
	v_mfma_f32_32x32x16_bf16 v[66:81], v[110:113], v[142:145], v[66:81]
	v_cvt_pk_bf16_f32 v110, v233, v235
	v_cvt_pk_bf16_f32 v111, v237, v239
	v_cvt_pk_bf16_f32 v112, v241, v243
	v_cvt_pk_bf16_f32 v113, v183, v200
	s_waitcnt lgkmcnt(0)
	v_mfma_f32_32x32x16_bf16 v[82:97], v[98:101], v[142:145], v[82:97]
	s_add_i32 s10, s4, 1
	s_cmp_lg_u32 s4, 2
	s_cselect_b32 s62, s10, 0
	s_add_i32 s4, s5, 1
	s_cmp_lg_u32 s5, 2
	s_cselect_b32 s10, s4, 0
	s_add_i32 s34, s34, 2
	v_add_f32_e32 v198, v179, v254
	v_cvt_pk_bf16_f32 v98, v231, v234
	v_cvt_pk_bf16_f32 v99, v236, v238
	v_cvt_pk_bf16_f32 v100, v240, v242
	v_cvt_pk_bf16_f32 v101, v181, v195
	s_cmp_ge_i32 s61, s48
	s_cbranch_scc1 .LBB0_473
	s_mov_b32 s60, s63
	s_add_i32 s61, s34, -2
	s_cmp_gt_i32 s61, s48
	s_mov_b64 s[4:5], -1
	s_cbranch_scc1 .LBB0_451
